# row-statistics exchange: 4 granule polls issued together (one wait) instead of 4 serialized round trips; v0-5 spilled to LDS around the loop
# baseline (speedup 1.0000x reference)
.LBB0_614:
	s_or_b64 exec, exec, s[20:21]
	v_add_u32_e32 v196, 0x80, v98
	v_ashrrev_i32_e32 v197, 31, v196
	v_lshlrev_b64 v[232:233], 11, v[196:197]
	v_lshl_add_u64 v[164:165], s[6:7], 0, v[232:233]
	v_lshlrev_b64 v[226:227], 1, v[224:225]
	v_lshl_add_u64 v[164:165], v[164:165], 0, v[226:227]
	global_load_dwordx4 v[208:211], v[164:165], off
	global_load_dwordx4 v[204:207], v[164:165], off offset:256
	v_add_u32_e32 v164, 0x90, v98
	s_add_i32 s15, s24, 0xffffe000
	v_ashrrev_i32_e32 v165, 31, v164
	s_ashr_i32 s15, s15, 11
	v_lshlrev_b64 v[230:231], 11, v[164:165]
	s_add_i32 s15, s15, 1
	v_lshl_add_u64 v[164:165], s[6:7], 0, v[230:231]
	s_add_u32 s19, s16, s13
	v_lshl_add_u64 v[164:165], v[164:165], 0, v[226:227]
	s_addc_u32 s20, s17, 0
	global_load_dwordx4 v[200:203], v[164:165], off
	global_load_dwordx4 v[192:195], v[164:165], off offset:256
	v_add_u32_e32 v164, 0xa0, v98
	s_cmp_gt_i32 s18, 31
	v_ashrrev_i32_e32 v165, 31, v164
	s_cselect_b32 s15, s15, 0
	v_lshlrev_b64 v[228:229], 11, v[164:165]
	v_lshl_add_u64 v[164:165], s[6:7], 0, v[228:229]
	s_mul_hi_i32 s6, s15, 0x6000
	s_mulk_i32 s15, 0x6000
	s_add_u32 s7, s19, s15
	s_addc_u32 s6, s20, s6
	s_add_u32 s18, s7, 0x4e00000
	v_lshl_add_u64 v[164:165], v[164:165], 0, v[226:227]
	s_addc_u32 s19, s6, 0
	global_load_dwordx4 v[184:187], v[164:165], off
	global_load_dwordx4 v[180:183], v[164:165], off offset:256
	v_lshl_add_u64 v[164:165], v[224:225], 2, s[18:19]
	s_mov_b64 s[6:7], 0x2000
	v_lshl_add_u64 v[168:169], v[164:165], 0, s[6:7]
	v_add_co_u32_e32 v164, vcc, 0x2000, v164
	v_mov_b32_e32 v197, 0x100000
	s_nop 0
	v_addc_co_u32_e32 v165, vcc, 0, v165, vcc
	global_load_dwordx4 v[172:175], v[164:165], off
	s_nop 0
	global_load_dwordx4 v[164:167], v[168:169], off offset:528
	global_load_dwordx4 v[176:179], v[168:169], off offset:16
	s_nop 0
	global_load_dwordx4 v[168:171], v[168:169], off offset:512
	s_mov_b32 s101, m0
	v_readfirstlane_b32 s100, v214
	s_nop 3
	s_mul_i32 s100, s100, 4
	s_bitset1_b32 s100, 15
	s_mov_b32 m0, s100
	s_nop 0
	ds_write_addtid_b32 v0 offset:0
	ds_write_addtid_b32 v1 offset:2048
	ds_write_addtid_b32 v2 offset:4096
	ds_write_addtid_b32 v3 offset:6144
	ds_write_addtid_b32 v4 offset:8192
	ds_write_addtid_b32 v5 offset:10240
	s_waitcnt lgkmcnt(0)
	s_branch .LBB0_616

.LBB0_616:
	s_mov_b64 s[20:21], -1
	v_mov_b32_e32 v198, 0x358637bd
	s_mov_b64 s[6:7], -1
	s_and_saveexec_b64 s[22:23], s[2:3]
	s_cbranch_execz .LBB0_618
	global_load_dwordx2 v[0:1], v[190:191], off sc1
	global_load_dwordx2 v[2:3], v[190:191], off offset:8 sc1
	global_load_dwordx2 v[4:5], v[190:191], off offset:16 sc1
	global_load_dwordx2 v[198:199], v[190:191], off offset:24 sc1
	s_waitcnt vmcnt(0)
	v_cmp_eq_u32_e32 vcc, s66, v1
	v_cmp_eq_u32_e64 s[6:7], s66, v3
	v_add_f32_e32 v212, 0, v0
	v_add_f32_e32 v212, v212, v2
	s_and_b64 s[6:7], vcc, s[6:7]
	v_cmp_eq_u32_e32 vcc, s66, v5
	v_add_f32_e32 v212, v212, v4
	s_nop 0
	s_and_b64 s[6:7], s[6:7], vcc
	v_cmp_eq_u32_e32 vcc, s66, v199
	v_add_f32_e32 v198, v212, v198
	v_fmamk_f32 v198, v198, 0x3a800000, v251
	s_and_b64 s[6:7], s[6:7], vcc
	s_orn2_b64 s[6:7], s[6:7], exec

.LBB0_620:
	ds_read_addtid_b32 v0 offset:0
	ds_read_addtid_b32 v1 offset:2048
	ds_read_addtid_b32 v2 offset:4096
	ds_read_addtid_b32 v3 offset:6144
	ds_read_addtid_b32 v4 offset:8192
	ds_read_addtid_b32 v5 offset:10240
	s_waitcnt lgkmcnt(0)
	s_mov_b32 m0, s101
	s_nop 0
	v_lshl_add_u32 v99, v99, 2, 0
	s_and_saveexec_b64 s[6:7], s[2:3]
	v_rsq_f32_e32 v190, v198
	ds_write_b32 v99, v190 offset:4096
	s_or_b64 exec, exec, s[6:7]
	v_add_u32_e32 v190, 48, v196
	v_ashrrev_i32_e32 v191, 31, v190
	v_lshlrev_b64 v[190:191], 11, v[190:191]
	s_waitcnt lgkmcnt(0)
	s_barrier
	v_lshl_add_u64 v[188:189], v[188:189], 0, v[190:191]
	global_load_dwordx4 v[196:199], v[188:189], off
	s_nop 0
	global_load_dwordx4 v[188:191], v[188:189], off offset:256
	s_lshl_b32 s6, s34, 8
	s_add_i32 s20, s6, 0
	v_lshl_add_u32 v212, v238, 2, s20
	v_add_u32_e32 v212, 0x1000, v212
	ds_read2_b32 v[236:237], v212 offset1:16
	s_waitcnt vmcnt(0)
	v_lshlrev_b32_e32 v240, 16, v160
	v_and_b32_e32 v241, 0xffff0000, v160
	v_lshlrev_b32_e32 v160, 16, v161
	v_and_b32_e32 v161, 0xffff0000, v161
	s_waitcnt lgkmcnt(0)
	v_pk_mul_f32 v[130:131], v[130:131], v[236:237] op_sel_hi:[1,0]
	v_lshlrev_b32_e32 v242, 16, v162
	v_and_b32_e32 v243, 0xffff0000, v162
	v_lshlrev_b32_e32 v162, 16, v163
	v_and_b32_e32 v163, 0xffff0000, v163
	v_pk_mul_f32 v[244:245], v[128:129], v[236:237] op_sel_hi:[1,0]
	v_pk_fma_f32 v[128:129], v[174:175], v[130:131], v[160:161]
	v_pk_mul_f32 v[126:127], v[126:127], v[236:237] op_sel_hi:[1,0]
	v_pk_mul_f32 v[160:161], v[124:125], v[236:237] op_sel_hi:[1,0]
	v_pk_fma_f32 v[124:125], v[178:179], v[126:127], v[162:163]
	v_pk_fma_f32 v[126:127], v[176:177], v[160:161], v[242:243]
	v_lshlrev_b32_e32 v160, 16, v156
	v_and_b32_e32 v161, 0xffff0000, v156
	v_lshlrev_b32_e32 v156, 16, v157
	v_and_b32_e32 v157, 0xffff0000, v157
	v_pk_mul_f32 v[122:123], v[122:123], v[236:237] op_sel_hi:[1,0]
	v_pk_fma_f32 v[130:131], v[172:173], v[244:245], v[240:241]
	v_lshlrev_b32_e32 v162, 16, v158
	v_and_b32_e32 v163, 0xffff0000, v158
	v_lshlrev_b32_e32 v158, 16, v159
	v_and_b32_e32 v159, 0xffff0000, v159
	v_pk_mul_f32 v[240:241], v[120:121], v[236:237] op_sel_hi:[1,0]
	v_pk_fma_f32 v[120:121], v[170:171], v[122:123], v[156:157]
	v_pk_mul_f32 v[118:119], v[118:119], v[236:237] op_sel_hi:[1,0]
	v_pk_mul_f32 v[156:157], v[116:117], v[236:237] op_sel_hi:[1,0]
	v_pk_fma_f32 v[116:117], v[166:167], v[118:119], v[158:159]
	v_pk_fma_f32 v[118:119], v[164:165], v[156:157], v[162:163]
	v_mul_f32_e32 v162, v131, v131
	v_mul_f32_e32 v163, v129, v129
	v_fmac_f32_e32 v162, v130, v130
	v_fmac_f32_e32 v163, v128, v128
	v_pk_fma_f32 v[122:123], v[168:169], v[240:241], v[160:161]
	ds_read2_b32 v[160:161], v212 offset0:32 offset1:48
	ds_read2_b32 v[158:159], v212 offset0:128 offset1:144
	ds_read2_b32 v[156:157], v212 offset0:160 offset1:176
	v_add_f32_e32 v162, v162, v163
	v_mul_f32_e32 v163, v127, v127
	v_mul_f32_e32 v212, v125, v125
	v_fmac_f32_e32 v163, v126, v126
	v_fmac_f32_e32 v212, v124, v124
	v_add_f32_e32 v163, v163, v212
	v_add_f32_e32 v162, v162, v163
	v_mul_f32_e32 v163, v123, v123
	v_mul_f32_e32 v212, v121, v121
	v_fmac_f32_e32 v163, v122, v122
	v_fmac_f32_e32 v212, v120, v120
	v_add_f32_e32 v163, v163, v212
	v_add_f32_e32 v162, v163, v162
	v_mul_f32_e32 v163, v119, v119
	v_mul_f32_e32 v212, v117, v117
	v_fmac_f32_e32 v163, v118, v118
	v_fmac_f32_e32 v212, v116, v116
	v_add_f32_e32 v163, v163, v212
	v_add_f32_e32 v162, v163, v162
	v_mov_b32_e32 v163, v162
	s_nop 1
	v_permlane16_swap_b32_e32 v162, v163
	v_add_f32_e32 v162, v162, v163
	v_mov_b32_e32 v163, v162
	s_nop 1
	v_permlane32_swap_b32_e32 v162, v163
	s_and_saveexec_b64 s[6:7], s[4:5]
	s_lshl_b32 s15, s34, 10
	s_add_i32 s15, s35, s15
	v_lshl_add_u32 v212, v238, 4, s15
	v_add_f32_e32 v162, v162, v163
	ds_write_b32 v212, v162
	s_or_b64 exec, exec, s[6:7]
	v_mov_b32_e32 v236, v237
	v_lshlrev_b32_e32 v162, 16, v152
	v_and_b32_e32 v163, 0xffff0000, v152
	v_lshlrev_b32_e32 v152, 16, v153
	v_and_b32_e32 v153, 0xffff0000, v153
	v_pk_mul_f32 v[114:115], v[114:115], v[236:237] op_sel_hi:[1,0]
	v_lshlrev_b32_e32 v240, 16, v154
	v_and_b32_e32 v241, 0xffff0000, v154
	v_lshlrev_b32_e32 v154, 16, v155
	v_and_b32_e32 v155, 0xffff0000, v155
	v_pk_mul_f32 v[242:243], v[112:113], v[236:237] op_sel_hi:[1,0]
	v_pk_fma_f32 v[112:113], v[174:175], v[114:115], v[152:153]
	v_pk_mul_f32 v[110:111], v[110:111], v[236:237] op_sel_hi:[1,0]
	v_pk_mul_f32 v[152:153], v[108:109], v[236:237] op_sel_hi:[1,0]
	v_pk_fma_f32 v[108:109], v[178:179], v[110:111], v[154:155]
	v_pk_fma_f32 v[110:111], v[176:177], v[152:153], v[240:241]
	v_lshlrev_b32_e32 v152, 16, v148
	v_and_b32_e32 v153, 0xffff0000, v148
	v_lshlrev_b32_e32 v148, 16, v149
	v_and_b32_e32 v149, 0xffff0000, v149
	v_pk_mul_f32 v[106:107], v[106:107], v[236:237] op_sel_hi:[1,0]
	v_pk_fma_f32 v[114:115], v[172:173], v[242:243], v[162:163]
	v_lshlrev_b32_e32 v154, 16, v150
	v_and_b32_e32 v155, 0xffff0000, v150
	v_lshlrev_b32_e32 v150, 16, v151
	v_and_b32_e32 v151, 0xffff0000, v151
	v_pk_mul_f32 v[162:163], v[104:105], v[236:237] op_sel_hi:[1,0]
	v_pk_fma_f32 v[104:105], v[170:171], v[106:107], v[148:149]
	v_pk_mul_f32 v[102:103], v[102:103], v[236:237] op_sel_hi:[1,0]
	v_pk_mul_f32 v[148:149], v[100:101], v[236:237] op_sel_hi:[1,0]
	v_pk_fma_f32 v[100:101], v[166:167], v[102:103], v[150:151]
	v_pk_fma_f32 v[102:103], v[164:165], v[148:149], v[154:155]
	v_mul_f32_e32 v148, v115, v115
	v_mul_f32_e32 v149, v113, v113
	v_fmac_f32_e32 v148, v114, v114
	v_fmac_f32_e32 v149, v112, v112
	v_add_f32_e32 v148, v148, v149
	v_mul_f32_e32 v149, v111, v111
	v_mul_f32_e32 v150, v109, v109
	v_fmac_f32_e32 v149, v110, v110
	v_fmac_f32_e32 v150, v108, v108
	v_pk_fma_f32 v[106:107], v[168:169], v[162:163], v[152:153]
	v_add_f32_e32 v149, v149, v150
	v_add_f32_e32 v148, v148, v149
	v_mul_f32_e32 v149, v107, v107
	v_mul_f32_e32 v150, v105, v105
	v_fmac_f32_e32 v149, v106, v106
	v_fmac_f32_e32 v150, v104, v104
	v_add_f32_e32 v149, v149, v150
	v_add_f32_e32 v148, v149, v148
	v_mul_f32_e32 v149, v103, v103
	v_mul_f32_e32 v150, v101, v101
	v_fmac_f32_e32 v149, v102, v102
	v_fmac_f32_e32 v150, v100, v100
	v_add_f32_e32 v149, v149, v150
	v_add_f32_e32 v148, v149, v148
	v_mov_b32_e32 v149, v148
	s_nop 1
	v_permlane16_swap_b32_e32 v148, v149
	v_add_f32_e32 v148, v148, v149
	v_mov_b32_e32 v149, v148
	s_nop 1
	v_permlane32_swap_b32_e32 v148, v149
	s_and_saveexec_b64 s[6:7], s[4:5]
	s_lshl_b32 s15, s34, 10
	s_add_i32 s15, s35, s15
	v_lshl_add_u32 v150, v238, 4, s15
	v_add_f32_e32 v148, v148, v149
	ds_write_b32 v150, v148 offset:256
	s_or_b64 exec, exec, s[6:7]
	v_lshlrev_b32_e32 v148, 16, v144
	v_and_b32_e32 v149, 0xffff0000, v144
	v_lshlrev_b32_e32 v144, 16, v145
	v_and_b32_e32 v145, 0xffff0000, v145
	s_waitcnt lgkmcnt(2)
	v_pk_mul_f32 v[94:95], v[94:95], v[160:161] op_sel_hi:[1,0]
	v_lshlrev_b32_e32 v150, 16, v146
	v_and_b32_e32 v151, 0xffff0000, v146
	v_lshlrev_b32_e32 v146, 16, v147
	v_and_b32_e32 v147, 0xffff0000, v147
	v_pk_mul_f32 v[152:153], v[92:93], v[160:161] op_sel_hi:[1,0]
	v_pk_fma_f32 v[92:93], v[174:175], v[94:95], v[144:145]
	v_pk_mul_f32 v[90:91], v[90:91], v[160:161] op_sel_hi:[1,0]
	v_pk_mul_f32 v[144:145], v[88:89], v[160:161] op_sel_hi:[1,0]
	v_pk_fma_f32 v[88:89], v[178:179], v[90:91], v[146:147]
	v_pk_fma_f32 v[90:91], v[176:177], v[144:145], v[150:151]
	v_lshlrev_b32_e32 v144, 16, v140
	v_and_b32_e32 v145, 0xffff0000, v140
	v_lshlrev_b32_e32 v140, 16, v141
	v_and_b32_e32 v141, 0xffff0000, v141
	v_pk_mul_f32 v[86:87], v[86:87], v[160:161] op_sel_hi:[1,0]
	v_pk_fma_f32 v[94:95], v[172:173], v[152:153], v[148:149]
	v_lshlrev_b32_e32 v146, 16, v142
	v_and_b32_e32 v147, 0xffff0000, v142
	v_lshlrev_b32_e32 v142, 16, v143
	v_and_b32_e32 v143, 0xffff0000, v143
	v_pk_mul_f32 v[148:149], v[84:85], v[160:161] op_sel_hi:[1,0]
	v_pk_fma_f32 v[84:85], v[170:171], v[86:87], v[140:141]
	v_pk_mul_f32 v[82:83], v[82:83], v[160:161] op_sel_hi:[1,0]
	v_pk_mul_f32 v[140:141], v[80:81], v[160:161] op_sel_hi:[1,0]
	v_pk_fma_f32 v[80:81], v[166:167], v[82:83], v[142:143]
	v_pk_fma_f32 v[82:83], v[164:165], v[140:141], v[146:147]
	v_mul_f32_e32 v140, v95, v95
	v_mul_f32_e32 v141, v93, v93
	v_fmac_f32_e32 v140, v94, v94
	v_fmac_f32_e32 v141, v92, v92
	v_add_f32_e32 v140, v140, v141
	v_mul_f32_e32 v141, v91, v91
	v_mul_f32_e32 v142, v89, v89
	v_fmac_f32_e32 v141, v90, v90
	v_fmac_f32_e32 v142, v88, v88
	v_pk_fma_f32 v[86:87], v[168:169], v[148:149], v[144:145]
	v_add_f32_e32 v141, v141, v142
	v_add_f32_e32 v140, v140, v141
	v_mul_f32_e32 v141, v87, v87
	v_mul_f32_e32 v142, v85, v85
	v_fmac_f32_e32 v141, v86, v86
	v_fmac_f32_e32 v142, v84, v84
	v_add_f32_e32 v141, v141, v142
	v_add_f32_e32 v140, v141, v140
	v_mul_f32_e32 v141, v83, v83
	v_mul_f32_e32 v142, v81, v81
	v_fmac_f32_e32 v141, v82, v82
	v_fmac_f32_e32 v142, v80, v80
	v_add_f32_e32 v141, v141, v142
	v_add_f32_e32 v140, v141, v140
	v_mov_b32_e32 v141, v140
	s_nop 1
	v_permlane16_swap_b32_e32 v140, v141
	v_add_f32_e32 v140, v140, v141
	v_mov_b32_e32 v141, v140
	s_nop 1
	v_permlane32_swap_b32_e32 v140, v141
	s_and_saveexec_b64 s[6:7], s[4:5]
	s_lshl_b32 s15, s34, 10
	s_add_i32 s15, s35, s15
	v_lshl_add_u32 v142, v238, 4, s15
	v_add_f32_e32 v140, v140, v141
	ds_write_b32 v142, v140 offset:512
	s_or_b64 exec, exec, s[6:7]
	v_mov_b32_e32 v144, v161
	v_lshlrev_b32_e32 v140, 16, v136
	v_and_b32_e32 v141, 0xffff0000, v136
	v_lshlrev_b32_e32 v136, 16, v137
	v_and_b32_e32 v137, 0xffff0000, v137
	v_pk_mul_f32 v[78:79], v[78:79], v[144:145] op_sel_hi:[1,0]
	v_lshlrev_b32_e32 v142, 16, v138
	v_and_b32_e32 v143, 0xffff0000, v138
	v_lshlrev_b32_e32 v138, 16, v139
	v_and_b32_e32 v139, 0xffff0000, v139
	v_pk_mul_f32 v[146:147], v[76:77], v[144:145] op_sel_hi:[1,0]
	v_pk_fma_f32 v[76:77], v[174:175], v[78:79], v[136:137]
	v_pk_mul_f32 v[74:75], v[74:75], v[144:145] op_sel_hi:[1,0]
	v_pk_mul_f32 v[136:137], v[72:73], v[144:145] op_sel_hi:[1,0]
	v_pk_fma_f32 v[72:73], v[178:179], v[74:75], v[138:139]
	v_pk_fma_f32 v[74:75], v[176:177], v[136:137], v[142:143]
	v_lshlrev_b32_e32 v136, 16, v132
	v_and_b32_e32 v137, 0xffff0000, v132
	v_lshlrev_b32_e32 v132, 16, v133
	v_and_b32_e32 v133, 0xffff0000, v133
	v_pk_mul_f32 v[70:71], v[70:71], v[144:145] op_sel_hi:[1,0]
	v_pk_fma_f32 v[78:79], v[172:173], v[146:147], v[140:141]
	v_lshlrev_b32_e32 v138, 16, v134
	v_and_b32_e32 v139, 0xffff0000, v134
	v_lshlrev_b32_e32 v134, 16, v135
	v_and_b32_e32 v135, 0xffff0000, v135
	v_pk_mul_f32 v[140:141], v[68:69], v[144:145] op_sel_hi:[1,0]
	v_pk_fma_f32 v[68:69], v[170:171], v[70:71], v[132:133]
	v_pk_mul_f32 v[66:67], v[66:67], v[144:145] op_sel_hi:[1,0]
	v_pk_mul_f32 v[132:133], v[64:65], v[144:145] op_sel_hi:[1,0]
	v_pk_fma_f32 v[64:65], v[166:167], v[66:67], v[134:135]
	v_pk_fma_f32 v[66:67], v[164:165], v[132:133], v[138:139]
	v_mul_f32_e32 v132, v79, v79
	v_mul_f32_e32 v133, v77, v77
	v_fmac_f32_e32 v132, v78, v78
	v_fmac_f32_e32 v133, v76, v76
	v_add_f32_e32 v132, v132, v133
	v_mul_f32_e32 v133, v75, v75
	v_mul_f32_e32 v134, v73, v73
	v_fmac_f32_e32 v133, v74, v74
	v_fmac_f32_e32 v134, v72, v72
	v_pk_fma_f32 v[70:71], v[168:169], v[140:141], v[136:137]
	v_add_f32_e32 v133, v133, v134
	v_add_f32_e32 v132, v132, v133
	v_mul_f32_e32 v133, v71, v71
	v_mul_f32_e32 v134, v69, v69
	v_fmac_f32_e32 v133, v70, v70
	v_fmac_f32_e32 v134, v68, v68
	v_add_f32_e32 v133, v133, v134
	v_add_f32_e32 v132, v133, v132
	v_mul_f32_e32 v133, v67, v67
	v_mul_f32_e32 v134, v65, v65
	v_fmac_f32_e32 v133, v66, v66
	v_fmac_f32_e32 v134, v64, v64
	v_add_f32_e32 v133, v133, v134
	v_add_f32_e32 v132, v133, v132
	v_mov_b32_e32 v133, v132
	s_nop 1
	v_permlane16_swap_b32_e32 v132, v133
	v_add_f32_e32 v132, v132, v133
	v_mov_b32_e32 v133, v132
	s_nop 1
	v_permlane32_swap_b32_e32 v132, v133
	s_and_saveexec_b64 s[6:7], s[4:5]
	s_lshl_b32 s15, s34, 10
	s_add_i32 s15, s35, s15
	v_lshl_add_u32 v134, v238, 4, s15
	v_add_f32_e32 v132, v132, v133
	ds_write_b32 v134, v132 offset:768
	s_or_b64 exec, exec, s[6:7]
	v_lshlrev_b32_e32 v132, 16, v208
	v_and_b32_e32 v133, 0xffff0000, v208
	v_lshlrev_b32_e32 v134, 16, v209
	v_and_b32_e32 v135, 0xffff0000, v209
	s_waitcnt lgkmcnt(1)
	v_pk_mul_f32 v[62:63], v[62:63], v[158:159] op_sel_hi:[1,0]
	v_pk_mul_f32 v[140:141], v[60:61], v[158:159] op_sel_hi:[1,0]
	v_lshlrev_b32_e32 v136, 16, v210
	v_and_b32_e32 v137, 0xffff0000, v210
	v_lshlrev_b32_e32 v138, 16, v211
	v_and_b32_e32 v139, 0xffff0000, v211
	v_pk_fma_f32 v[60:61], v[174:175], v[62:63], v[134:135]
	v_pk_fma_f32 v[62:63], v[172:173], v[140:141], v[132:133]
	v_pk_mul_f32 v[58:59], v[58:59], v[158:159] op_sel_hi:[1,0]
	v_pk_mul_f32 v[132:133], v[56:57], v[158:159] op_sel_hi:[1,0]
	v_pk_fma_f32 v[56:57], v[178:179], v[58:59], v[138:139]
	v_pk_fma_f32 v[58:59], v[176:177], v[132:133], v[136:137]
	v_lshlrev_b32_e32 v132, 16, v204
	v_and_b32_e32 v133, 0xffff0000, v204
	v_lshlrev_b32_e32 v134, 16, v205
	v_and_b32_e32 v135, 0xffff0000, v205
	v_pk_mul_f32 v[54:55], v[54:55], v[158:159] op_sel_hi:[1,0]
	v_pk_mul_f32 v[140:141], v[52:53], v[158:159] op_sel_hi:[1,0]
	v_lshlrev_b32_e32 v136, 16, v206
	v_and_b32_e32 v137, 0xffff0000, v206
	v_lshlrev_b32_e32 v138, 16, v207
	v_and_b32_e32 v139, 0xffff0000, v207
	v_pk_fma_f32 v[52:53], v[170:171], v[54:55], v[134:135]
	v_pk_fma_f32 v[54:55], v[168:169], v[140:141], v[132:133]
	v_pk_mul_f32 v[50:51], v[50:51], v[158:159] op_sel_hi:[1,0]
	v_pk_mul_f32 v[132:133], v[48:49], v[158:159] op_sel_hi:[1,0]
	v_pk_fma_f32 v[48:49], v[166:167], v[50:51], v[138:139]
	v_pk_fma_f32 v[50:51], v[164:165], v[132:133], v[136:137]
	v_mul_f32_e32 v132, v63, v63
	v_mul_f32_e32 v133, v61, v61
	v_fmac_f32_e32 v132, v62, v62
	v_fmac_f32_e32 v133, v60, v60
	v_add_f32_e32 v132, v132, v133
	v_mul_f32_e32 v133, v59, v59
	v_mul_f32_e32 v134, v57, v57
	v_fmac_f32_e32 v133, v58, v58
	v_fmac_f32_e32 v134, v56, v56
	v_add_f32_e32 v133, v133, v134
	v_add_f32_e32 v132, v132, v133
	v_mul_f32_e32 v133, v55, v55
	v_mul_f32_e32 v134, v53, v53
	v_fmac_f32_e32 v133, v54, v54
	v_fmac_f32_e32 v134, v52, v52
	v_add_f32_e32 v133, v133, v134
	v_add_f32_e32 v132, v133, v132
	v_mul_f32_e32 v133, v51, v51
	v_mul_f32_e32 v134, v49, v49
	v_fmac_f32_e32 v133, v50, v50
	v_fmac_f32_e32 v134, v48, v48
	v_add_f32_e32 v133, v133, v134
	v_add_f32_e32 v132, v133, v132
	v_mov_b32_e32 v133, v132
	s_nop 1
	v_permlane16_swap_b32_e32 v132, v133
	v_add_f32_e32 v132, v132, v133
	v_mov_b32_e32 v133, v132
	s_nop 1
	v_permlane32_swap_b32_e32 v132, v133
	s_and_saveexec_b64 s[6:7], s[4:5]
	s_lshl_b32 s15, s34, 10
	s_add_i32 s15, s35, s15
	v_lshl_add_u32 v134, v238, 4, s15
	v_add_f32_e32 v132, v132, v133
	ds_write_b32 v134, v132 offset:2048
	s_or_b64 exec, exec, s[6:7]
	v_mov_b32_e32 v140, v159
	v_lshlrev_b32_e32 v132, 16, v200
	v_and_b32_e32 v133, 0xffff0000, v200
	v_lshlrev_b32_e32 v134, 16, v201
	v_and_b32_e32 v135, 0xffff0000, v201
	v_pk_mul_f32 v[46:47], v[46:47], v[140:141] op_sel_hi:[1,0]
	v_pk_mul_f32 v[142:143], v[44:45], v[140:141] op_sel_hi:[1,0]
	v_lshlrev_b32_e32 v136, 16, v202
	v_and_b32_e32 v137, 0xffff0000, v202
	v_lshlrev_b32_e32 v138, 16, v203
	v_and_b32_e32 v139, 0xffff0000, v203
	v_pk_fma_f32 v[44:45], v[174:175], v[46:47], v[134:135]
	v_pk_fma_f32 v[46:47], v[172:173], v[142:143], v[132:133]
	v_pk_mul_f32 v[42:43], v[42:43], v[140:141] op_sel_hi:[1,0]
	v_pk_mul_f32 v[132:133], v[40:41], v[140:141] op_sel_hi:[1,0]
	v_pk_fma_f32 v[40:41], v[178:179], v[42:43], v[138:139]
	v_pk_fma_f32 v[42:43], v[176:177], v[132:133], v[136:137]
	v_lshlrev_b32_e32 v132, 16, v192
	v_and_b32_e32 v133, 0xffff0000, v192
	v_lshlrev_b32_e32 v134, 16, v193
	v_and_b32_e32 v135, 0xffff0000, v193
	v_pk_mul_f32 v[38:39], v[38:39], v[140:141] op_sel_hi:[1,0]
	v_pk_mul_f32 v[142:143], v[36:37], v[140:141] op_sel_hi:[1,0]
	v_lshlrev_b32_e32 v136, 16, v194
	v_and_b32_e32 v137, 0xffff0000, v194
	v_lshlrev_b32_e32 v138, 16, v195
	v_and_b32_e32 v139, 0xffff0000, v195
	v_pk_fma_f32 v[36:37], v[170:171], v[38:39], v[134:135]
	v_pk_fma_f32 v[38:39], v[168:169], v[142:143], v[132:133]
	v_pk_mul_f32 v[34:35], v[34:35], v[140:141] op_sel_hi:[1,0]
	v_pk_mul_f32 v[132:133], v[32:33], v[140:141] op_sel_hi:[1,0]
	v_pk_fma_f32 v[32:33], v[166:167], v[34:35], v[138:139]
	v_pk_fma_f32 v[34:35], v[164:165], v[132:133], v[136:137]
	v_mul_f32_e32 v132, v47, v47
	v_mul_f32_e32 v133, v45, v45
	v_fmac_f32_e32 v132, v46, v46
	v_fmac_f32_e32 v133, v44, v44
	v_add_f32_e32 v132, v132, v133
	v_mul_f32_e32 v133, v43, v43
	v_mul_f32_e32 v134, v41, v41
	v_fmac_f32_e32 v133, v42, v42
	v_fmac_f32_e32 v134, v40, v40
	v_add_f32_e32 v133, v133, v134
	v_add_f32_e32 v132, v132, v133
	v_mul_f32_e32 v133, v39, v39
	v_mul_f32_e32 v134, v37, v37
	v_fmac_f32_e32 v133, v38, v38
	v_fmac_f32_e32 v134, v36, v36
	v_add_f32_e32 v133, v133, v134
	v_add_f32_e32 v132, v133, v132
	v_mul_f32_e32 v133, v35, v35
	v_mul_f32_e32 v134, v33, v33
	v_fmac_f32_e32 v133, v34, v34
	v_fmac_f32_e32 v134, v32, v32
	v_add_f32_e32 v133, v133, v134
	v_add_f32_e32 v132, v133, v132
	v_mov_b32_e32 v133, v132
	s_nop 1
	v_permlane16_swap_b32_e32 v132, v133
	v_add_f32_e32 v132, v132, v133
	v_mov_b32_e32 v133, v132
	s_nop 1
	v_permlane32_swap_b32_e32 v132, v133
	s_and_saveexec_b64 s[6:7], s[4:5]
	s_lshl_b32 s15, s34, 10
	s_add_i32 s15, s35, s15
	v_lshl_add_u32 v134, v238, 4, s15
	v_add_f32_e32 v132, v132, v133
	ds_write_b32 v134, v132 offset:2304
	s_or_b64 exec, exec, s[6:7]
	v_lshlrev_b32_e32 v134, 16, v184
	v_and_b32_e32 v135, 0xffff0000, v184
	v_lshlrev_b32_e32 v132, 16, v185
	v_and_b32_e32 v133, 0xffff0000, v185
	s_waitcnt lgkmcnt(0)
	v_pk_mul_f32 v[30:31], v[30:31], v[156:157] op_sel_hi:[1,0]
	v_pk_mul_f32 v[28:29], v[28:29], v[156:157] op_sel_hi:[1,0]
	v_pk_fma_f32 v[132:133], v[174:175], v[30:31], v[132:133]
	v_pk_fma_f32 v[134:135], v[172:173], v[28:29], v[134:135]
	v_lshlrev_b32_e32 v28, 16, v182
	v_and_b32_e32 v29, 0xffff0000, v182
	v_pk_mul_f32 v[16:17], v[16:17], v[156:157] op_sel_hi:[1,0]
	v_lshlrev_b32_e32 v136, 16, v186
	v_and_b32_e32 v137, 0xffff0000, v186
	v_lshlrev_b32_e32 v138, 16, v187
	v_and_b32_e32 v139, 0xffff0000, v187
	v_pk_mul_f32 v[26:27], v[26:27], v[156:157] op_sel_hi:[1,0]
	v_pk_mul_f32 v[24:25], v[24:25], v[156:157] op_sel_hi:[1,0]
	v_pk_fma_f32 v[146:147], v[164:165], v[16:17], v[28:29]
	v_mul_f32_e32 v16, v135, v135
	v_mul_f32_e32 v17, v133, v133
	v_pk_fma_f32 v[140:141], v[178:179], v[26:27], v[138:139]
	v_pk_fma_f32 v[142:143], v[176:177], v[24:25], v[136:137]
	v_lshlrev_b32_e32 v30, 16, v183
	v_and_b32_e32 v31, 0xffff0000, v183
	v_pk_mul_f32 v[18:19], v[18:19], v[156:157] op_sel_hi:[1,0]
	v_fmac_f32_e32 v16, v134, v134
	v_fmac_f32_e32 v17, v132, v132
	v_pk_fma_f32 v[144:145], v[166:167], v[18:19], v[30:31]
	v_add_f32_e32 v16, v16, v17
	v_mul_f32_e32 v17, v143, v143
	v_mul_f32_e32 v18, v141, v141
	v_lshlrev_b32_e32 v24, 16, v180
	v_and_b32_e32 v25, 0xffff0000, v180
	v_lshlrev_b32_e32 v26, 16, v181
	v_and_b32_e32 v27, 0xffff0000, v181
	v_pk_mul_f32 v[22:23], v[22:23], v[156:157] op_sel_hi:[1,0]
	v_pk_mul_f32 v[20:21], v[20:21], v[156:157] op_sel_hi:[1,0]
	v_fmac_f32_e32 v17, v142, v142
	v_fmac_f32_e32 v18, v140, v140
	v_pk_fma_f32 v[136:137], v[170:171], v[22:23], v[26:27]
	v_pk_fma_f32 v[138:139], v[168:169], v[20:21], v[24:25]
	v_add_f32_e32 v17, v17, v18
	v_add_f32_e32 v16, v16, v17
	v_mul_f32_e32 v17, v139, v139
	v_mul_f32_e32 v18, v137, v137
	v_fmac_f32_e32 v17, v138, v138
	v_fmac_f32_e32 v18, v136, v136
	v_add_f32_e32 v17, v17, v18
	v_add_f32_e32 v16, v17, v16
	v_mul_f32_e32 v17, v147, v147
	v_mul_f32_e32 v18, v145, v145
	v_fmac_f32_e32 v17, v146, v146
	v_fmac_f32_e32 v18, v144, v144
	v_add_f32_e32 v17, v17, v18
	v_add_f32_e32 v16, v17, v16
	v_mov_b32_e32 v17, v16
	s_nop 1
	v_permlane16_swap_b32_e32 v16, v17
	v_add_f32_e32 v16, v16, v17
	v_mov_b32_e32 v17, v16
	s_nop 1
	v_permlane32_swap_b32_e32 v16, v17
	s_and_saveexec_b64 s[6:7], s[4:5]
	s_lshl_b32 s15, s34, 10
	s_add_i32 s15, s35, s15
	v_lshl_add_u32 v18, v238, 4, s15
	v_add_f32_e32 v16, v16, v17
	ds_write_b32 v18, v16 offset:2560
	s_or_b64 exec, exec, s[6:7]
	v_mov_b32_e32 v24, v157
	v_lshlrev_b32_e32 v16, 16, v196
	v_and_b32_e32 v17, 0xffff0000, v196
	v_lshlrev_b32_e32 v18, 16, v197
	v_and_b32_e32 v19, 0xffff0000, v197
	v_pk_mul_f32 v[14:15], v[14:15], v[24:25] op_sel_hi:[1,0]
	v_pk_mul_f32 v[12:13], v[12:13], v[24:25] op_sel_hi:[1,0]
	v_pk_fma_f32 v[150:151], v[174:175], v[14:15], v[18:19]
	v_pk_fma_f32 v[154:155], v[172:173], v[12:13], v[16:17]
	v_lshlrev_b32_e32 v12, 16, v190
	v_and_b32_e32 v13, 0xffff0000, v190
	v_pk_mul_f32 v[0:1], v[0:1], v[24:25] op_sel_hi:[1,0]
	v_lshlrev_b32_e32 v20, 16, v198
	v_and_b32_e32 v21, 0xffff0000, v198
	v_lshlrev_b32_e32 v22, 16, v199
	v_and_b32_e32 v23, 0xffff0000, v199
	v_pk_mul_f32 v[10:11], v[10:11], v[24:25] op_sel_hi:[1,0]
	v_pk_mul_f32 v[8:9], v[8:9], v[24:25] op_sel_hi:[1,0]
	v_pk_fma_f32 v[160:161], v[164:165], v[0:1], v[12:13]
	v_mul_f32_e32 v0, v155, v155
	v_mul_f32_e32 v1, v151, v151
	v_pk_fma_f32 v[158:159], v[178:179], v[10:11], v[22:23]
	v_pk_fma_f32 v[162:163], v[176:177], v[8:9], v[20:21]
	v_lshlrev_b32_e32 v14, 16, v191
	v_and_b32_e32 v15, 0xffff0000, v191
	v_pk_mul_f32 v[2:3], v[2:3], v[24:25] op_sel_hi:[1,0]
	v_fmac_f32_e32 v0, v154, v154
	v_fmac_f32_e32 v1, v150, v150
	v_pk_fma_f32 v[156:157], v[166:167], v[2:3], v[14:15]
	v_add_f32_e32 v0, v0, v1
	v_mul_f32_e32 v1, v163, v163
	v_mul_f32_e32 v2, v159, v159
	v_lshlrev_b32_e32 v8, 16, v188
	v_and_b32_e32 v9, 0xffff0000, v188
	v_lshlrev_b32_e32 v10, 16, v189
	v_and_b32_e32 v11, 0xffff0000, v189
	v_pk_mul_f32 v[6:7], v[6:7], v[24:25] op_sel_hi:[1,0]
	v_pk_mul_f32 v[4:5], v[4:5], v[24:25] op_sel_hi:[1,0]
	v_fmac_f32_e32 v1, v162, v162
	v_fmac_f32_e32 v2, v158, v158
	v_pk_fma_f32 v[148:149], v[170:171], v[6:7], v[10:11]
	v_pk_fma_f32 v[152:153], v[168:169], v[4:5], v[8:9]
	v_add_f32_e32 v1, v1, v2
	v_add_f32_e32 v0, v0, v1
	v_mul_f32_e32 v1, v153, v153
	v_mul_f32_e32 v2, v149, v149
	v_fmac_f32_e32 v1, v152, v152
	v_fmac_f32_e32 v2, v148, v148
	v_add_f32_e32 v1, v1, v2
	v_add_f32_e32 v0, v1, v0
	v_mul_f32_e32 v1, v161, v161
	v_mul_f32_e32 v2, v157, v157
	v_fmac_f32_e32 v1, v160, v160
	v_fmac_f32_e32 v2, v156, v156
	v_add_f32_e32 v1, v1, v2
	v_add_f32_e32 v0, v1, v0
	v_mov_b32_e32 v1, v0
	s_nop 1
	v_permlane16_swap_b32_e32 v0, v1
	v_add_f32_e32 v0, v0, v1
	v_mov_b32_e32 v1, v0
	s_nop 1
	v_permlane32_swap_b32_e32 v0, v1
	s_and_saveexec_b64 s[6:7], s[4:5]
	s_lshl_b32 s4, s34, 10
	s_add_i32 s35, s35, s4
	v_lshl_add_u32 v2, v238, 4, s35
	v_add_f32_e32 v0, v0, v1
	ds_write_b32 v2, v0 offset:2816
	s_or_b64 exec, exec, s[6:7]
	s_waitcnt lgkmcnt(0)
	s_barrier
	s_mov_b64 s[4:5], 0x4f80000
	s_or_b32 s21, s63, 2
	v_lshl_add_u64 v[164:165], v[234:235], 0, s[4:5]
	s_and_saveexec_b64 s[4:5], s[2:3]
	s_cbranch_execz .LBB0_640
	ds_read_b128 v[0:3], v239
	s_ashr_i32 s15, s14, 31
	s_waitcnt lgkmcnt(0)
	v_mov_b32_e32 v4, v1
	v_mov_b32_e32 v5, v2
	v_mov_b32_e32 v1, v3
	v_pk_add_f32 v[0:1], v[4:5], v[0:1]
	v_lshl_add_u64 v[2:3], s[14:15], 3, v[164:165]
	v_pk_add_f32 v[0:1], v[0:1], v[0:1] op_sel:[0,1] op_sel_hi:[1,0]
	s_nop 0
	v_mov_b32_e32 v1, s21
	global_store_dwordx2 v[2:3], v[0:1], off sc1
.LBB0_640:
	s_or_b64 exec, exec, s[4:5]
	s_add_i32 s4, s41, -2
	s_cmp_lt_u32 s4, 4
	s_cselect_b32 s4, 0x2000000, 0
	s_add_u32 s4, s27, s4
	s_addc_u32 s5, s62, 0
	s_add_u32 s6, s18, 0x3000
	s_addc_u32 s7, s19, 0
	s_add_u32 s14, s18, 0x4000
	s_addc_u32 s15, s19, 0
	v_lshlrev_b64 v[0:1], 2, v[224:225]
	v_lshl_add_u64 v[2:3], s[14:15], 0, v[0:1]
	v_lshl_add_u64 v[0:1], s[6:7], 0, v[0:1]
	global_load_dwordx4 v[4:7], v[2:3], off offset:16
	global_load_dwordx4 v[12:15], v[2:3], off
	global_load_dwordx4 v[20:23], v[0:1], off offset:16
	global_load_dwordx4 v[28:31], v[0:1], off
	v_add_u32_e32 v0, 0x80, v224
	v_ashrrev_i32_e32 v1, 31, v0
	v_lshlrev_b64 v[16:17], 2, v[0:1]
	v_lshl_add_u64 v[8:9], s[14:15], 0, v[16:17]
	v_lshl_add_u64 v[24:25], s[6:7], 0, v[16:17]
	global_load_dwordx4 v[0:3], v[8:9], off offset:16
	s_nop 0
	global_load_dwordx4 v[8:11], v[8:9], off
	s_nop 0
	global_load_dwordx4 v[16:19], v[24:25], off offset:16
	s_nop 0
	global_load_dwordx4 v[24:27], v[24:25], off
	v_lshl_add_u64 v[170:171], s[4:5], 0, v[222:223]
	v_cvt_pk_bf16_f32 v166, v130, v131
	v_cvt_pk_bf16_f32 v167, v128, v129
	v_cvt_pk_bf16_f32 v168, v126, v127
	v_cvt_pk_bf16_f32 v169, v124, v125
	v_lshl_add_u64 v[170:171], v[170:171], 0, v[226:227]
	global_store_dwordx4 v[170:171], v[166:169], off
	s_nop 1
	v_cvt_pk_bf16_f32 v166, v122, v123
	v_cvt_pk_bf16_f32 v167, v120, v121
	v_cvt_pk_bf16_f32 v168, v118, v119
	v_cvt_pk_bf16_f32 v169, v116, v117
	global_store_dwordx4 v[170:171], v[166:169], off offset:256
	v_lshl_add_u64 v[170:171], s[4:5], 0, v[220:221]
	v_lshl_add_u64 v[170:171], v[170:171], 0, v[226:227]
	v_cvt_pk_bf16_f32 v166, v114, v115
	v_cvt_pk_bf16_f32 v167, v112, v113
	v_cvt_pk_bf16_f32 v168, v110, v111
	v_cvt_pk_bf16_f32 v169, v108, v109
	global_store_dwordx4 v[170:171], v[166:169], off
	s_nop 1
	v_cvt_pk_bf16_f32 v166, v106, v107
	v_cvt_pk_bf16_f32 v167, v104, v105
	v_cvt_pk_bf16_f32 v168, v102, v103
	v_cvt_pk_bf16_f32 v169, v100, v101
	global_store_dwordx4 v[170:171], v[166:169], off offset:256
	v_lshl_add_u64 v[170:171], s[4:5], 0, v[218:219]
	v_lshl_add_u64 v[170:171], v[170:171], 0, v[226:227]
	v_cvt_pk_bf16_f32 v166, v94, v95
	v_cvt_pk_bf16_f32 v167, v92, v93
	v_cvt_pk_bf16_f32 v168, v90, v91
	v_cvt_pk_bf16_f32 v169, v88, v89
	global_store_dwordx4 v[170:171], v[166:169], off
	s_nop 1
	v_cvt_pk_bf16_f32 v166, v86, v87
	v_cvt_pk_bf16_f32 v167, v84, v85
	v_cvt_pk_bf16_f32 v168, v82, v83
	v_cvt_pk_bf16_f32 v169, v80, v81
	global_store_dwordx4 v[170:171], v[166:169], off offset:256
	v_lshl_add_u64 v[170:171], s[4:5], 0, v[216:217]
	v_lshl_add_u64 v[170:171], v[170:171], 0, v[226:227]
	v_cvt_pk_bf16_f32 v166, v78, v79
	v_cvt_pk_bf16_f32 v167, v76, v77
	v_cvt_pk_bf16_f32 v168, v74, v75
	v_cvt_pk_bf16_f32 v169, v72, v73
	global_store_dwordx4 v[170:171], v[166:169], off
	s_nop 1
	v_cvt_pk_bf16_f32 v166, v70, v71
	v_cvt_pk_bf16_f32 v167, v68, v69
	v_cvt_pk_bf16_f32 v168, v66, v67
	v_cvt_pk_bf16_f32 v169, v64, v65
	global_store_dwordx4 v[170:171], v[166:169], off offset:256
	v_lshl_add_u64 v[170:171], s[4:5], 0, v[232:233]
	v_lshl_add_u64 v[170:171], v[170:171], 0, v[226:227]
	v_cvt_pk_bf16_f32 v166, v62, v63
	v_cvt_pk_bf16_f32 v167, v60, v61
	v_cvt_pk_bf16_f32 v168, v58, v59
	v_cvt_pk_bf16_f32 v169, v56, v57
	global_store_dwordx4 v[170:171], v[166:169], off
	s_nop 1
	v_cvt_pk_bf16_f32 v166, v54, v55
	v_cvt_pk_bf16_f32 v167, v52, v53
	v_cvt_pk_bf16_f32 v168, v50, v51
	v_cvt_pk_bf16_f32 v169, v48, v49
	global_store_dwordx4 v[170:171], v[166:169], off offset:256
	v_lshl_add_u64 v[170:171], s[4:5], 0, v[230:231]
	v_lshl_add_u64 v[170:171], v[170:171], 0, v[226:227]
	v_cvt_pk_bf16_f32 v166, v46, v47
	v_cvt_pk_bf16_f32 v167, v44, v45
	v_cvt_pk_bf16_f32 v168, v42, v43
	v_cvt_pk_bf16_f32 v169, v40, v41
	global_store_dwordx4 v[170:171], v[166:169], off
	s_nop 1
	v_cvt_pk_bf16_f32 v166, v38, v39
	v_cvt_pk_bf16_f32 v167, v36, v37
	v_cvt_pk_bf16_f32 v168, v34, v35
	v_cvt_pk_bf16_f32 v169, v32, v33
	global_store_dwordx4 v[170:171], v[166:169], off offset:256
	v_lshl_add_u64 v[170:171], s[4:5], 0, v[228:229]
	v_lshl_add_u64 v[170:171], v[170:171], 0, v[226:227]
	v_cvt_pk_bf16_f32 v166, v134, v135
	v_cvt_pk_bf16_f32 v167, v132, v133
	v_cvt_pk_bf16_f32 v168, v142, v143
	v_cvt_pk_bf16_f32 v169, v140, v141
	global_store_dwordx4 v[170:171], v[166:169], off
	s_nop 1
	v_cvt_pk_bf16_f32 v166, v138, v139
	v_cvt_pk_bf16_f32 v167, v136, v137
	v_cvt_pk_bf16_f32 v168, v146, v147
	v_cvt_pk_bf16_f32 v169, v144, v145
	global_store_dwordx4 v[170:171], v[166:169], off offset:256
	s_nop 1
	v_add_u32_e32 v166, 0xb0, v98
	v_ashrrev_i32_e32 v167, 31, v166
	v_lshlrev_b64 v[170:171], 11, v[166:167]
	v_lshl_add_u64 v[170:171], s[4:5], 0, v[170:171]
	v_cvt_pk_bf16_f32 v166, v154, v155
	v_cvt_pk_bf16_f32 v167, v150, v151
	v_cvt_pk_bf16_f32 v168, v162, v163
	v_cvt_pk_bf16_f32 v169, v158, v159
	v_lshl_add_u64 v[170:171], v[170:171], 0, v[226:227]
	v_mov_b32_e32 v98, 0x100000
	global_store_dwordx4 v[170:171], v[166:169], off
	s_nop 1
	v_cvt_pk_bf16_f32 v166, v152, v153
	v_cvt_pk_bf16_f32 v167, v148, v149
	v_cvt_pk_bf16_f32 v168, v160, v161
	v_cvt_pk_bf16_f32 v169, v156, v157
	global_store_dwordx4 v[170:171], v[166:169], off offset:256
	s_mov_b32 s101, m0
	v_readfirstlane_b32 s100, v214
	s_nop 3
	s_mul_i32 s100, s100, 4
	s_bitset1_b32 s100, 15
	s_mov_b32 m0, s100
	s_nop 0
	ds_write_addtid_b32 v0 offset:0
	ds_write_addtid_b32 v1 offset:2048
	ds_write_addtid_b32 v2 offset:4096
	ds_write_addtid_b32 v3 offset:6144
	ds_write_addtid_b32 v4 offset:8192
	ds_write_addtid_b32 v5 offset:10240
	s_waitcnt lgkmcnt(0)
	s_branch .LBB0_642

.LBB0_642:
	s_mov_b64 s[6:7], -1
	v_mov_b32_e32 v166, 0x358637bd
	s_mov_b64 s[4:5], -1
	s_and_saveexec_b64 s[14:15], s[2:3]
	s_cbranch_execz .LBB0_644
	global_load_dwordx2 v[0:1], v[164:165], off sc1
	global_load_dwordx2 v[2:3], v[164:165], off offset:8 sc1
	global_load_dwordx2 v[4:5], v[164:165], off offset:16 sc1
	global_load_dwordx2 v[166:167], v[164:165], off offset:24 sc1
	s_waitcnt vmcnt(0)
	v_cmp_eq_u32_e32 vcc, s21, v1
	v_cmp_eq_u32_e64 s[4:5], s21, v3
	v_add_f32_e32 v168, 0, v0
	v_add_f32_e32 v168, v168, v2
	s_and_b64 s[4:5], vcc, s[4:5]
	v_cmp_eq_u32_e32 vcc, s21, v5
	v_add_f32_e32 v168, v168, v4
	s_nop 0
	s_and_b64 s[4:5], s[4:5], vcc
	v_cmp_eq_u32_e32 vcc, s21, v167
	v_add_f32_e32 v166, v168, v166
	v_fmamk_f32 v166, v166, 0x3a800000, v251
	s_and_b64 s[4:5], s[4:5], vcc
	s_orn2_b64 s[4:5], s[4:5], exec

.LBB0_646:
	ds_read_addtid_b32 v0 offset:0
	ds_read_addtid_b32 v1 offset:2048
	ds_read_addtid_b32 v2 offset:4096
	ds_read_addtid_b32 v3 offset:6144
	ds_read_addtid_b32 v4 offset:8192
	ds_read_addtid_b32 v5 offset:10240
	s_waitcnt lgkmcnt(0)
	s_mov_b32 m0, s101
	s_nop 0
	s_and_saveexec_b64 s[4:5], s[2:3]
	v_rsq_f32_e32 v98, v166
	ds_write_b32 v99, v98 offset:4096
	s_or_b64 exec, exec, s[4:5]
	s_waitcnt lgkmcnt(0)
	s_barrier
	s_add_i32 s24, s24, s25
	v_lshl_add_u32 v170, v238, 2, s20
	v_lshl_add_u32 v98, v96, 3, s26
	ds_read_b32 v96, v170 offset:4096
	v_ashrrev_i32_e32 v99, 31, v98
	v_add_u32_e32 v164, s24, v238
	v_lshl_add_u64 v[98:99], v[98:99], 1, s[16:17]
	s_mov_b64 s[2:3], 0x5000000
	v_ashrrev_i32_e32 v165, 31, v164
	v_lshl_add_u64 v[98:99], v[98:99], 0, s[2:3]
	v_lshlrev_b64 v[166:167], 11, v[164:165]
	s_waitcnt lgkmcnt(0)
	v_pk_mul_f32 v[128:129], v[128:129], v[96:97] op_sel_hi:[1,0]
	v_pk_mul_f32 v[130:131], v[130:131], v[96:97] op_sel_hi:[1,0]
	v_pk_mul_f32 v[124:125], v[124:125], v[96:97] op_sel_hi:[1,0]
	v_pk_mul_f32 v[126:127], v[126:127], v[96:97] op_sel_hi:[1,0]
	v_pk_mul_f32 v[118:119], v[118:119], v[96:97] op_sel_hi:[1,0]
	v_lshl_add_u64 v[166:167], v[98:99], 0, v[166:167]
	s_waitcnt vmcnt(20)
	v_pk_fma_f32 v[128:129], v[14:15], v[128:129], v[30:31]
	v_pk_fma_f32 v[130:131], v[12:13], v[130:131], v[28:29]
	v_pk_fma_f32 v[126:127], v[4:5], v[126:127], v[20:21]
	v_pk_fma_f32 v[168:169], v[6:7], v[124:125], v[22:23]
	v_cvt_pk_bf16_f32 v124, v130, v131
	v_cvt_pk_bf16_f32 v125, v128, v129
	v_pk_mul_f32 v[120:121], v[120:121], v[96:97] op_sel_hi:[1,0]
	v_pk_mul_f32 v[122:123], v[122:123], v[96:97] op_sel_hi:[1,0]
	v_pk_mul_f32 v[116:117], v[116:117], v[96:97] op_sel_hi:[1,0]
	s_waitcnt vmcnt(17)
	v_pk_fma_f32 v[118:119], v[0:1], v[118:119], v[16:17]
	v_cvt_pk_bf16_f32 v126, v126, v127
	v_cvt_pk_bf16_f32 v127, v168, v169
	global_store_dwordx4 v[166:167], v[124:127], off
	s_waitcnt vmcnt(17)
	v_pk_fma_f32 v[120:121], v[10:11], v[120:121], v[26:27]
	v_pk_fma_f32 v[122:123], v[8:9], v[122:123], v[24:25]
	v_pk_fma_f32 v[124:125], v[2:3], v[116:117], v[18:19]
	v_cvt_pk_bf16_f32 v116, v122, v123
	v_cvt_pk_bf16_f32 v117, v120, v121
	v_cvt_pk_bf16_f32 v118, v118, v119
	s_nop 0
	v_cvt_pk_bf16_f32 v119, v124, v125
	global_store_dwordx4 v[166:167], v[116:119], off offset:256
	ds_read_b32 v96, v170 offset:4160
	s_waitcnt lgkmcnt(0)
	v_pk_mul_f32 v[112:113], v[112:113], v[96:97] op_sel_hi:[1,0]
	v_add_u32_e32 v116, 16, v164
	v_ashrrev_i32_e32 v117, 31, v116
	v_lshlrev_b64 v[116:117], 11, v[116:117]
	v_pk_mul_f32 v[114:115], v[114:115], v[96:97] op_sel_hi:[1,0]
	v_pk_mul_f32 v[108:109], v[108:109], v[96:97] op_sel_hi:[1,0]
	v_pk_mul_f32 v[110:111], v[110:111], v[96:97] op_sel_hi:[1,0]
	v_pk_mul_f32 v[102:103], v[102:103], v[96:97] op_sel_hi:[1,0]
	v_lshl_add_u64 v[116:117], v[98:99], 0, v[116:117]
	v_pk_fma_f32 v[112:113], v[14:15], v[112:113], v[30:31]
	v_pk_fma_f32 v[114:115], v[12:13], v[114:115], v[28:29]
	v_pk_fma_f32 v[110:111], v[4:5], v[110:111], v[20:21]
	v_pk_fma_f32 v[118:119], v[6:7], v[108:109], v[22:23]
	v_cvt_pk_bf16_f32 v108, v114, v115
	v_cvt_pk_bf16_f32 v109, v112, v113
	v_pk_mul_f32 v[104:105], v[104:105], v[96:97] op_sel_hi:[1,0]
	v_pk_mul_f32 v[106:107], v[106:107], v[96:97] op_sel_hi:[1,0]
	v_pk_mul_f32 v[100:101], v[100:101], v[96:97] op_sel_hi:[1,0]
	v_pk_fma_f32 v[102:103], v[0:1], v[102:103], v[16:17]
	v_cvt_pk_bf16_f32 v110, v110, v111
	v_cvt_pk_bf16_f32 v111, v118, v119
	global_store_dwordx4 v[116:117], v[108:111], off
	v_pk_fma_f32 v[104:105], v[10:11], v[104:105], v[26:27]
	v_pk_fma_f32 v[106:107], v[8:9], v[106:107], v[24:25]
	v_pk_fma_f32 v[108:109], v[2:3], v[100:101], v[18:19]
	v_cvt_pk_bf16_f32 v100, v106, v107
	v_cvt_pk_bf16_f32 v101, v104, v105
	v_cvt_pk_bf16_f32 v102, v102, v103
	s_nop 0
	v_cvt_pk_bf16_f32 v103, v108, v109
	global_store_dwordx4 v[116:117], v[100:103], off offset:256
	ds_read_b32 v96, v170 offset:4224
	s_waitcnt lgkmcnt(0)
	v_pk_mul_f32 v[92:93], v[92:93], v[96:97] op_sel_hi:[1,0]
	v_add_u32_e32 v100, 32, v164
	v_ashrrev_i32_e32 v101, 31, v100
	v_lshlrev_b64 v[100:101], 11, v[100:101]
	v_pk_mul_f32 v[94:95], v[94:95], v[96:97] op_sel_hi:[1,0]
	v_pk_mul_f32 v[88:89], v[88:89], v[96:97] op_sel_hi:[1,0]
	v_pk_mul_f32 v[90:91], v[90:91], v[96:97] op_sel_hi:[1,0]
	v_pk_mul_f32 v[82:83], v[82:83], v[96:97] op_sel_hi:[1,0]
	v_lshl_add_u64 v[100:101], v[98:99], 0, v[100:101]
	v_pk_fma_f32 v[92:93], v[14:15], v[92:93], v[30:31]
	v_pk_fma_f32 v[94:95], v[12:13], v[94:95], v[28:29]
	v_pk_fma_f32 v[90:91], v[4:5], v[90:91], v[20:21]
	v_pk_fma_f32 v[102:103], v[6:7], v[88:89], v[22:23]
	v_cvt_pk_bf16_f32 v88, v94, v95
	v_cvt_pk_bf16_f32 v89, v92, v93
	v_pk_mul_f32 v[84:85], v[84:85], v[96:97] op_sel_hi:[1,0]
	v_pk_mul_f32 v[86:87], v[86:87], v[96:97] op_sel_hi:[1,0]
	v_pk_mul_f32 v[80:81], v[80:81], v[96:97] op_sel_hi:[1,0]
	v_pk_fma_f32 v[82:83], v[0:1], v[82:83], v[16:17]
	v_cvt_pk_bf16_f32 v90, v90, v91
	v_cvt_pk_bf16_f32 v91, v102, v103
	global_store_dwordx4 v[100:101], v[88:91], off
	v_pk_fma_f32 v[84:85], v[10:11], v[84:85], v[26:27]
	v_pk_fma_f32 v[86:87], v[8:9], v[86:87], v[24:25]
	v_pk_fma_f32 v[88:89], v[2:3], v[80:81], v[18:19]
	v_cvt_pk_bf16_f32 v80, v86, v87
	v_cvt_pk_bf16_f32 v81, v84, v85
	v_cvt_pk_bf16_f32 v82, v82, v83
	s_nop 0
	v_cvt_pk_bf16_f32 v83, v88, v89
	global_store_dwordx4 v[100:101], v[80:83], off offset:256
	ds_read_b32 v80, v170 offset:4288
	s_waitcnt lgkmcnt(0)
	v_pk_mul_f32 v[76:77], v[76:77], v[80:81] op_sel_hi:[1,0]
	v_add_u32_e32 v82, 48, v164
	v_ashrrev_i32_e32 v83, 31, v82
	v_lshlrev_b64 v[82:83], 11, v[82:83]
	v_pk_mul_f32 v[78:79], v[78:79], v[80:81] op_sel_hi:[1,0]
	v_pk_mul_f32 v[72:73], v[72:73], v[80:81] op_sel_hi:[1,0]
	v_pk_mul_f32 v[74:75], v[74:75], v[80:81] op_sel_hi:[1,0]
	v_pk_mul_f32 v[66:67], v[66:67], v[80:81] op_sel_hi:[1,0]
	v_lshl_add_u64 v[82:83], v[98:99], 0, v[82:83]
	v_pk_fma_f32 v[76:77], v[14:15], v[76:77], v[30:31]
	v_pk_fma_f32 v[78:79], v[12:13], v[78:79], v[28:29]
	v_pk_fma_f32 v[74:75], v[4:5], v[74:75], v[20:21]
	v_pk_fma_f32 v[84:85], v[6:7], v[72:73], v[22:23]
	v_cvt_pk_bf16_f32 v72, v78, v79
	v_cvt_pk_bf16_f32 v73, v76, v77
	v_pk_mul_f32 v[68:69], v[68:69], v[80:81] op_sel_hi:[1,0]
	v_pk_mul_f32 v[70:71], v[70:71], v[80:81] op_sel_hi:[1,0]
	v_pk_mul_f32 v[64:65], v[64:65], v[80:81] op_sel_hi:[1,0]
	v_pk_fma_f32 v[66:67], v[0:1], v[66:67], v[16:17]
	v_cvt_pk_bf16_f32 v74, v74, v75
	v_cvt_pk_bf16_f32 v75, v84, v85
	global_store_dwordx4 v[82:83], v[72:75], off
	v_pk_fma_f32 v[68:69], v[10:11], v[68:69], v[26:27]
	v_pk_fma_f32 v[70:71], v[8:9], v[70:71], v[24:25]
	v_pk_fma_f32 v[72:73], v[2:3], v[64:65], v[18:19]
	v_cvt_pk_bf16_f32 v64, v70, v71
	v_cvt_pk_bf16_f32 v65, v68, v69
	v_cvt_pk_bf16_f32 v66, v66, v67
	s_nop 0
	v_cvt_pk_bf16_f32 v67, v72, v73
	global_store_dwordx4 v[82:83], v[64:67], off offset:256
	ds_read_b32 v64, v170 offset:4608
	s_waitcnt lgkmcnt(0)
	v_pk_mul_f32 v[60:61], v[60:61], v[64:65] op_sel_hi:[1,0]
	v_add_u32_e32 v66, 0x80, v164
	v_ashrrev_i32_e32 v67, 31, v66
	v_lshlrev_b64 v[66:67], 11, v[66:67]
	v_pk_mul_f32 v[62:63], v[62:63], v[64:65] op_sel_hi:[1,0]
	v_pk_mul_f32 v[56:57], v[56:57], v[64:65] op_sel_hi:[1,0]
	v_pk_mul_f32 v[58:59], v[58:59], v[64:65] op_sel_hi:[1,0]
	v_pk_mul_f32 v[50:51], v[50:51], v[64:65] op_sel_hi:[1,0]
	v_lshl_add_u64 v[66:67], v[98:99], 0, v[66:67]
	v_pk_fma_f32 v[60:61], v[14:15], v[60:61], v[30:31]
	v_pk_fma_f32 v[62:63], v[12:13], v[62:63], v[28:29]
	v_pk_fma_f32 v[58:59], v[4:5], v[58:59], v[20:21]
	v_pk_fma_f32 v[68:69], v[6:7], v[56:57], v[22:23]
	v_cvt_pk_bf16_f32 v56, v62, v63
	v_cvt_pk_bf16_f32 v57, v60, v61
	v_pk_mul_f32 v[52:53], v[52:53], v[64:65] op_sel_hi:[1,0]
	v_pk_mul_f32 v[54:55], v[54:55], v[64:65] op_sel_hi:[1,0]
	v_pk_mul_f32 v[48:49], v[48:49], v[64:65] op_sel_hi:[1,0]
	v_pk_fma_f32 v[50:51], v[0:1], v[50:51], v[16:17]
	v_cvt_pk_bf16_f32 v58, v58, v59
	v_cvt_pk_bf16_f32 v59, v68, v69
	global_store_dwordx4 v[66:67], v[56:59], off
	v_pk_fma_f32 v[52:53], v[10:11], v[52:53], v[26:27]
	v_pk_fma_f32 v[54:55], v[8:9], v[54:55], v[24:25]
	v_pk_fma_f32 v[56:57], v[2:3], v[48:49], v[18:19]
	v_cvt_pk_bf16_f32 v48, v54, v55
	v_cvt_pk_bf16_f32 v49, v52, v53
	v_cvt_pk_bf16_f32 v50, v50, v51
	s_nop 0
	v_cvt_pk_bf16_f32 v51, v56, v57
	global_store_dwordx4 v[66:67], v[48:51], off offset:256
	ds_read_b32 v48, v170 offset:4672
	s_waitcnt lgkmcnt(0)
	v_pk_mul_f32 v[44:45], v[44:45], v[48:49] op_sel_hi:[1,0]
	v_add_u32_e32 v50, 0x90, v164
	v_ashrrev_i32_e32 v51, 31, v50
	v_lshlrev_b64 v[50:51], 11, v[50:51]
	v_pk_mul_f32 v[46:47], v[46:47], v[48:49] op_sel_hi:[1,0]
	v_pk_mul_f32 v[40:41], v[40:41], v[48:49] op_sel_hi:[1,0]
	v_pk_mul_f32 v[42:43], v[42:43], v[48:49] op_sel_hi:[1,0]
	v_pk_mul_f32 v[34:35], v[34:35], v[48:49] op_sel_hi:[1,0]
	v_lshl_add_u64 v[50:51], v[98:99], 0, v[50:51]
	v_pk_fma_f32 v[44:45], v[14:15], v[44:45], v[30:31]
	v_pk_fma_f32 v[46:47], v[12:13], v[46:47], v[28:29]
	v_pk_fma_f32 v[42:43], v[4:5], v[42:43], v[20:21]
	v_pk_fma_f32 v[52:53], v[6:7], v[40:41], v[22:23]
	v_cvt_pk_bf16_f32 v40, v46, v47
	v_cvt_pk_bf16_f32 v41, v44, v45
	v_pk_mul_f32 v[36:37], v[36:37], v[48:49] op_sel_hi:[1,0]
	v_pk_mul_f32 v[38:39], v[38:39], v[48:49] op_sel_hi:[1,0]
	v_pk_mul_f32 v[32:33], v[32:33], v[48:49] op_sel_hi:[1,0]
	v_pk_fma_f32 v[34:35], v[0:1], v[34:35], v[16:17]
	v_cvt_pk_bf16_f32 v42, v42, v43
	v_cvt_pk_bf16_f32 v43, v52, v53
	global_store_dwordx4 v[50:51], v[40:43], off
	v_pk_fma_f32 v[36:37], v[10:11], v[36:37], v[26:27]
	v_pk_fma_f32 v[38:39], v[8:9], v[38:39], v[24:25]
	v_pk_fma_f32 v[40:41], v[2:3], v[32:33], v[18:19]
	v_cvt_pk_bf16_f32 v32, v38, v39
	v_cvt_pk_bf16_f32 v33, v36, v37
	v_cvt_pk_bf16_f32 v34, v34, v35
	s_nop 0
	v_cvt_pk_bf16_f32 v35, v40, v41
	global_store_dwordx4 v[50:51], v[32:35], off offset:256
	ds_read_b32 v36, v170 offset:4736
	s_waitcnt lgkmcnt(0)
	v_pk_mul_f32 v[42:43], v[142:143], v[36:37] op_sel_hi:[1,0]
	v_add_u32_e32 v32, 0xa0, v164
	v_ashrrev_i32_e32 v33, 31, v32
	v_lshlrev_b64 v[32:33], 11, v[32:33]
	v_lshl_add_u64 v[38:39], v[98:99], 0, v[32:33]
	v_pk_mul_f32 v[32:33], v[132:133], v[36:37] op_sel_hi:[1,0]
	v_pk_mul_f32 v[34:35], v[134:135], v[36:37] op_sel_hi:[1,0]
	v_pk_fma_f32 v[40:41], v[14:15], v[32:33], v[30:31]
	v_pk_fma_f32 v[32:33], v[12:13], v[34:35], v[28:29]
	v_pk_mul_f32 v[34:35], v[140:141], v[36:37] op_sel_hi:[1,0]
	v_pk_fma_f32 v[42:43], v[4:5], v[42:43], v[20:21]
	v_pk_fma_f32 v[44:45], v[6:7], v[34:35], v[22:23]
	v_cvt_pk_bf16_f32 v32, v32, v33
	v_cvt_pk_bf16_f32 v33, v40, v41
	v_cvt_pk_bf16_f32 v34, v42, v43
	s_nop 0
	v_cvt_pk_bf16_f32 v35, v44, v45
	global_store_dwordx4 v[38:39], v[32:35], off
	s_nop 1
	v_pk_mul_f32 v[32:33], v[136:137], v[36:37] op_sel_hi:[1,0]
	v_pk_mul_f32 v[34:35], v[138:139], v[36:37] op_sel_hi:[1,0]
	v_pk_fma_f32 v[40:41], v[10:11], v[32:33], v[26:27]
	v_pk_fma_f32 v[32:33], v[8:9], v[34:35], v[24:25]
	v_pk_mul_f32 v[34:35], v[144:145], v[36:37] op_sel_hi:[1,0]
	v_pk_mul_f32 v[36:37], v[146:147], v[36:37] op_sel_hi:[1,0]
	v_pk_fma_f32 v[42:43], v[2:3], v[34:35], v[18:19]
	v_pk_fma_f32 v[36:37], v[0:1], v[36:37], v[16:17]
	v_cvt_pk_bf16_f32 v32, v32, v33
	v_cvt_pk_bf16_f32 v33, v40, v41
	s_nop 0
	v_cvt_pk_bf16_f32 v34, v36, v37
	v_cvt_pk_bf16_f32 v35, v42, v43
	global_store_dwordx4 v[38:39], v[32:35], off offset:256
	ds_read_b32 v32, v170 offset:4800
	s_waitcnt lgkmcnt(0)
	v_pk_mul_f32 v[36:37], v[150:151], v[32:33] op_sel_hi:[1,0]
	v_add_u32_e32 v34, 0xb0, v164
	v_ashrrev_i32_e32 v35, 31, v34
	v_pk_mul_f32 v[38:39], v[154:155], v[32:33] op_sel_hi:[1,0]
	v_lshlrev_b64 v[34:35], 11, v[34:35]
	v_pk_fma_f32 v[14:15], v[14:15], v[36:37], v[30:31]
	v_pk_fma_f32 v[12:13], v[12:13], v[38:39], v[28:29]
	v_pk_mul_f32 v[28:29], v[158:159], v[32:33] op_sel_hi:[1,0]
	v_pk_mul_f32 v[30:31], v[162:163], v[32:33] op_sel_hi:[1,0]
	v_lshl_add_u64 v[34:35], v[98:99], 0, v[34:35]
	v_pk_fma_f32 v[20:21], v[4:5], v[30:31], v[20:21]
	v_pk_fma_f32 v[22:23], v[6:7], v[28:29], v[22:23]
	v_cvt_pk_bf16_f32 v4, v12, v13
	v_cvt_pk_bf16_f32 v5, v14, v15
	v_cvt_pk_bf16_f32 v6, v20, v21
	s_nop 0
	v_cvt_pk_bf16_f32 v7, v22, v23
	global_store_dwordx4 v[34:35], v[4:7], off
	s_nop 1
	v_pk_mul_f32 v[4:5], v[148:149], v[32:33] op_sel_hi:[1,0]
	v_pk_mul_f32 v[6:7], v[152:153], v[32:33] op_sel_hi:[1,0]
	v_pk_fma_f32 v[4:5], v[10:11], v[4:5], v[26:27]
	v_pk_fma_f32 v[6:7], v[8:9], v[6:7], v[24:25]
	v_pk_mul_f32 v[8:9], v[156:157], v[32:33] op_sel_hi:[1,0]
	v_pk_mul_f32 v[10:11], v[160:161], v[32:33] op_sel_hi:[1,0]
	v_pk_fma_f32 v[8:9], v[2:3], v[8:9], v[18:19]
	v_pk_fma_f32 v[10:11], v[0:1], v[10:11], v[16:17]
	v_cvt_pk_bf16_f32 v0, v6, v7
	v_cvt_pk_bf16_f32 v1, v4, v5
	s_nop 0
	v_cvt_pk_bf16_f32 v2, v10, v11
	v_cvt_pk_bf16_f32 v3, v8, v9
	global_store_dwordx4 v[34:35], v[0:3], off offset:256

.LBB0_966:
	s_or_b64 exec, exec, s[22:23]
	s_add_u32 s69, s18, 0x4e00000
	s_addc_u32 s70, s19, 0
	s_add_i32 s21, s26, 0xffffe000
	s_ashr_i32 s21, s21, 11
	v_add_u32_e32 v202, 0x80, v210
	s_add_i32 s21, s21, 1
	v_ashrrev_i32_e32 v203, 31, v202
	s_add_u32 s13, s69, s13
	v_lshlrev_b64 v[242:243], 11, v[202:203]
	v_add_u32_e32 v224, 0x90, v210
	s_addc_u32 s22, s70, 0
	v_lshl_add_u64 v[150:151], s[6:7], 0, v[242:243]
	v_lshlrev_b64 v[236:237], 1, v[216:217]
	v_ashrrev_i32_e32 v225, 31, v224
	s_cmp_gt_i32 s63, 31
	v_lshl_add_u64 v[150:151], v[150:151], 0, v[236:237]
	v_lshlrev_b64 v[240:241], 11, v[224:225]
	v_add_u32_e32 v226, 0xa0, v210
	s_cselect_b32 s21, s21, 0
	global_load_dwordx4 v[206:209], v[150:151], off
	global_load_dwordx4 v[198:201], v[150:151], off offset:256
	v_lshl_add_u64 v[150:151], s[6:7], 0, v[240:241]
	v_ashrrev_i32_e32 v227, 31, v226
	v_lshl_add_u64 v[150:151], v[150:151], 0, v[236:237]
	v_lshlrev_b64 v[238:239], 11, v[226:227]
	s_mul_i32 s71, s21, 0x6000
	global_load_dwordx4 v[194:197], v[150:151], off
	global_load_dwordx4 v[186:189], v[150:151], off offset:256
	v_lshl_add_u64 v[150:151], s[6:7], 0, v[238:239]
	s_mul_hi_i32 s63, s21, 0x6000
	s_add_u32 s6, s13, s71
	v_lshl_add_u64 v[150:151], v[150:151], 0, v[236:237]
	s_addc_u32 s7, s22, s63
	global_load_dwordx4 v[182:185], v[150:151], off
	global_load_dwordx4 v[174:177], v[150:151], off offset:256
	v_lshl_add_u64 v[150:151], v[216:217], 2, s[6:7]
	s_mov_b64 s[6:7], 0x5000
	v_lshl_add_u64 v[154:155], v[150:151], 0, s[6:7]
	v_add_co_u32_e32 v150, vcc, 0x5000, v150
	v_mov_b32_e32 v203, 0x100000
	s_nop 0
	v_addc_co_u32_e32 v151, vcc, 0, v151, vcc
	global_load_dwordx4 v[166:169], v[150:151], off
	s_nop 0
	global_load_dwordx4 v[150:153], v[154:155], off offset:528
	global_load_dwordx4 v[162:165], v[154:155], off offset:16
	s_nop 0
	global_load_dwordx4 v[154:157], v[154:155], off offset:512
	s_mov_b32 s101, m0
	v_readfirstlane_b32 s100, v214
	s_nop 3
	s_mul_i32 s100, s100, 4
	s_bitset1_b32 s100, 15
	s_mov_b32 m0, s100
	s_nop 0
	ds_write_addtid_b32 v0 offset:0
	ds_write_addtid_b32 v1 offset:2048
	ds_write_addtid_b32 v2 offset:4096
	ds_write_addtid_b32 v3 offset:6144
	ds_write_addtid_b32 v4 offset:8192
	ds_write_addtid_b32 v5 offset:10240
	s_waitcnt lgkmcnt(0)
	s_branch .LBB0_968

.LBB0_968:
	s_mov_b64 s[22:23], -1
	v_mov_b32_e32 v204, 0x358637bd
	s_mov_b64 s[6:7], -1
	s_and_saveexec_b64 s[24:25], s[2:3]
	s_cbranch_execz .LBB0_970
	global_load_dwordx2 v[0:1], v[192:193], off sc1
	global_load_dwordx2 v[2:3], v[192:193], off offset:8 sc1
	global_load_dwordx2 v[4:5], v[192:193], off offset:16 sc1
	global_load_dwordx2 v[204:205], v[192:193], off offset:24 sc1
	s_waitcnt vmcnt(0)
	v_cmp_eq_u32_e32 vcc, s72, v1
	v_cmp_eq_u32_e64 s[6:7], s72, v3
	v_add_f32_e32 v212, 0, v0
	v_add_f32_e32 v212, v212, v2
	s_and_b64 s[6:7], vcc, s[6:7]
	v_cmp_eq_u32_e32 vcc, s72, v5
	v_add_f32_e32 v212, v212, v4
	s_nop 0
	s_and_b64 s[6:7], s[6:7], vcc
	v_cmp_eq_u32_e32 vcc, s72, v205
	v_add_f32_e32 v204, v212, v204
	v_fmamk_f32 v204, v204, 0x3a800000, v251
	s_and_b64 s[6:7], s[6:7], vcc
	s_orn2_b64 s[6:7], s[6:7], exec

.LBB0_972:
	ds_read_addtid_b32 v0 offset:0
	ds_read_addtid_b32 v1 offset:2048
	ds_read_addtid_b32 v2 offset:4096
	ds_read_addtid_b32 v3 offset:6144
	ds_read_addtid_b32 v4 offset:8192
	ds_read_addtid_b32 v5 offset:10240
	s_waitcnt lgkmcnt(0)
	s_mov_b32 m0, s101
	s_nop 0
	s_and_saveexec_b64 s[6:7], s[2:3]
	s_cbranch_execz .LBB0_974
	v_rsq_f32_e32 v192, v204
	v_lshl_add_u32 v193, v254, 2, 0
	ds_write_b32 v193, v192 offset:4096

.LBB0_993:
	s_or_b64 exec, exec, s[4:5]
	s_add_i32 s41, s41, -1
	s_cmp_lt_u32 s41, 4
	s_cselect_b32 s4, 0x2000000, 0
	s_add_u32 s4, s67, s4
	s_addc_u32 s5, s68, 0
	s_min_i32 s6, s36, 2
	s_mul_i32 s6, s6, 0x1e000
	s_add_u32 s6, s69, s6
	s_addc_u32 s7, s70, 0
	s_add_u32 s6, s6, s71
	s_addc_u32 s7, s7, s63
	s_add_u32 s22, s6, 0x1f000
	s_addc_u32 s23, s7, 0
	v_lshlrev_b64 v[134:135], 2, v[216:217]
	v_lshl_add_u64 v[136:137], s[22:23], 0, v[134:135]
	v_lshl_add_u64 v[134:135], s[6:7], 0, v[134:135]
	s_mov_b64 s[6:7], 0x1e000
	v_lshl_add_u64 v[150:151], v[134:135], 0, s[6:7]
	s_mov_b32 s6, 0x1e000
	v_add_co_u32_e32 v146, vcc, s6, v134
	v_add_u32_e32 v134, 0x80, v216
	s_nop 0
	v_addc_co_u32_e32 v147, vcc, 0, v135, vcc
	v_ashrrev_i32_e32 v135, 31, v134
	v_lshl_add_u64 v[142:143], v[134:135], 2, s[22:23]
	global_load_dwordx4 v[130:133], v[136:137], off offset:16
	global_load_dwordx4 v[138:141], v[136:137], off
	s_nop 0
	global_load_dwordx4 v[134:137], v[142:143], off offset:16
	s_nop 0
	global_load_dwordx4 v[142:145], v[142:143], off
	s_nop 0
	global_load_dwordx4 v[154:157], v[146:147], off
	s_nop 0
	global_load_dwordx4 v[146:149], v[150:151], off offset:528
	global_load_dwordx4 v[158:161], v[150:151], off offset:16
	s_nop 0
	global_load_dwordx4 v[150:153], v[150:151], off offset:512
	v_lshl_add_u64 v[168:169], s[4:5], 0, v[234:235]
	v_cvt_pk_bf16_f32 v164, v126, v127
	v_cvt_pk_bf16_f32 v165, v128, v129
	v_cvt_pk_bf16_f32 v166, v122, v123
	v_cvt_pk_bf16_f32 v167, v124, v125
	v_lshl_add_u64 v[168:169], v[168:169], 0, v[236:237]
	global_store_dwordx4 v[168:169], v[164:167], off
	s_nop 1
	v_cvt_pk_bf16_f32 v164, v114, v115
	v_cvt_pk_bf16_f32 v165, v116, v117
	v_cvt_pk_bf16_f32 v166, v106, v107
	v_cvt_pk_bf16_f32 v167, v108, v109
	global_store_dwordx4 v[168:169], v[164:167], off offset:256
	v_lshl_add_u64 v[168:169], s[4:5], 0, v[232:233]
	v_lshl_add_u64 v[168:169], v[168:169], 0, v[236:237]
	v_cvt_pk_bf16_f32 v164, v118, v119
	v_cvt_pk_bf16_f32 v165, v120, v121
	v_cvt_pk_bf16_f32 v166, v110, v111
	v_cvt_pk_bf16_f32 v167, v112, v113
	global_store_dwordx4 v[168:169], v[164:167], off
	s_nop 1
	v_cvt_pk_bf16_f32 v164, v98, v99
	v_cvt_pk_bf16_f32 v165, v100, v101
	v_cvt_pk_bf16_f32 v166, v88, v89
	v_cvt_pk_bf16_f32 v167, v90, v91
	global_store_dwordx4 v[168:169], v[164:167], off offset:256
	v_lshl_add_u64 v[168:169], s[4:5], 0, v[230:231]
	v_lshl_add_u64 v[168:169], v[168:169], 0, v[236:237]
	v_cvt_pk_bf16_f32 v164, v102, v103
	v_cvt_pk_bf16_f32 v165, v104, v105
	v_cvt_pk_bf16_f32 v166, v92, v93
	v_cvt_pk_bf16_f32 v167, v94, v95
	global_store_dwordx4 v[168:169], v[164:167], off
	s_nop 1
	v_cvt_pk_bf16_f32 v164, v80, v81
	v_cvt_pk_bf16_f32 v165, v82, v83
	v_cvt_pk_bf16_f32 v166, v72, v73
	v_cvt_pk_bf16_f32 v167, v74, v75
	global_store_dwordx4 v[168:169], v[164:167], off offset:256
	v_lshl_add_u64 v[168:169], s[4:5], 0, v[228:229]
	v_lshl_add_u64 v[168:169], v[168:169], 0, v[236:237]
	v_cvt_pk_bf16_f32 v164, v84, v85
	v_cvt_pk_bf16_f32 v165, v86, v87
	v_cvt_pk_bf16_f32 v166, v76, v77
	v_cvt_pk_bf16_f32 v167, v78, v79
	global_store_dwordx4 v[168:169], v[164:167], off
	s_nop 1
	v_cvt_pk_bf16_f32 v164, v68, v69
	v_cvt_pk_bf16_f32 v165, v70, v71
	v_cvt_pk_bf16_f32 v166, v64, v65
	v_cvt_pk_bf16_f32 v167, v66, v67
	global_store_dwordx4 v[168:169], v[164:167], off offset:256
	v_lshl_add_u64 v[168:169], s[4:5], 0, v[242:243]
	v_lshl_add_u64 v[168:169], v[168:169], 0, v[236:237]
	v_cvt_pk_bf16_f32 v164, v60, v61
	v_cvt_pk_bf16_f32 v165, v62, v63
	v_cvt_pk_bf16_f32 v166, v56, v57
	v_cvt_pk_bf16_f32 v167, v58, v59
	global_store_dwordx4 v[168:169], v[164:167], off
	s_nop 1
	v_cvt_pk_bf16_f32 v164, v48, v49
	v_cvt_pk_bf16_f32 v165, v50, v51
	v_cvt_pk_bf16_f32 v166, v40, v41
	v_cvt_pk_bf16_f32 v167, v42, v43
	global_store_dwordx4 v[168:169], v[164:167], off offset:256
	v_lshl_add_u64 v[168:169], s[4:5], 0, v[240:241]
	v_lshl_add_u64 v[168:169], v[168:169], 0, v[236:237]
	v_cvt_pk_bf16_f32 v164, v52, v53
	v_cvt_pk_bf16_f32 v165, v54, v55
	v_cvt_pk_bf16_f32 v166, v44, v45
	v_cvt_pk_bf16_f32 v167, v46, v47
	global_store_dwordx4 v[168:169], v[164:167], off
	s_nop 1
	v_cvt_pk_bf16_f32 v164, v32, v33
	v_cvt_pk_bf16_f32 v165, v34, v35
	v_cvt_pk_bf16_f32 v166, v24, v25
	v_cvt_pk_bf16_f32 v167, v26, v27
	global_store_dwordx4 v[168:169], v[164:167], off offset:256
	v_lshl_add_u64 v[168:169], s[4:5], 0, v[238:239]
	v_lshl_add_u64 v[168:169], v[168:169], 0, v[236:237]
	v_cvt_pk_bf16_f32 v164, v36, v37
	v_cvt_pk_bf16_f32 v165, v38, v39
	v_cvt_pk_bf16_f32 v166, v28, v29
	v_cvt_pk_bf16_f32 v167, v30, v31
	global_store_dwordx4 v[168:169], v[164:167], off
	s_nop 1
	v_cvt_pk_bf16_f32 v164, v16, v17
	v_cvt_pk_bf16_f32 v165, v18, v19
	v_cvt_pk_bf16_f32 v166, v8, v9
	v_cvt_pk_bf16_f32 v167, v10, v11
	global_store_dwordx4 v[168:169], v[164:167], off offset:256
	s_nop 1
	v_add_u32_e32 v164, 0xb0, v210
	v_ashrrev_i32_e32 v165, 31, v164
	v_lshlrev_b64 v[168:169], 11, v[164:165]
	v_lshl_add_u64 v[168:169], s[4:5], 0, v[168:169]
	v_cvt_pk_bf16_f32 v164, v20, v21
	v_lshl_add_u64 v[168:169], v[168:169], 0, v[236:237]
	v_cvt_pk_bf16_f32 v165, v22, v23
	v_cvt_pk_bf16_f32 v166, v12, v13
	v_cvt_pk_bf16_f32 v167, v14, v15
	global_store_dwordx4 v[168:169], v[164:167], off
	s_nop 1
	v_cvt_pk_bf16_f32 v164, v4, v5
	v_cvt_pk_bf16_f32 v165, v6, v7
	v_cvt_pk_bf16_f32 v166, v0, v1
	v_cvt_pk_bf16_f32 v167, v2, v3
	global_store_dwordx4 v[168:169], v[164:167], off offset:256
	s_nop 1
	v_mov_b32_e32 v164, 0x100000
	s_mov_b32 s101, m0
	v_readfirstlane_b32 s100, v214
	s_nop 3
	s_mul_i32 s100, s100, 4
	s_bitset1_b32 s100, 15
	s_mov_b32 m0, s100
	s_nop 0
	ds_write_addtid_b32 v0 offset:0
	ds_write_addtid_b32 v1 offset:2048
	ds_write_addtid_b32 v2 offset:4096
	ds_write_addtid_b32 v3 offset:6144
	ds_write_addtid_b32 v4 offset:8192
	ds_write_addtid_b32 v5 offset:10240
	s_waitcnt lgkmcnt(0)
	s_branch .LBB0_995

.LBB0_995:
	s_mov_b64 s[6:7], -1
	v_mov_b32_e32 v165, 0x358637bd
	s_mov_b64 s[4:5], -1
	s_and_saveexec_b64 s[22:23], s[2:3]
	s_cbranch_execz .LBB0_997
	global_load_dwordx2 v[0:1], v[162:163], off sc1
	global_load_dwordx2 v[2:3], v[162:163], off offset:8 sc1
	global_load_dwordx2 v[4:5], v[162:163], off offset:16 sc1
	global_load_dwordx2 v[166:167], v[162:163], off offset:24 sc1
	s_waitcnt vmcnt(0)
	v_cmp_eq_u32_e32 vcc, s35, v1
	v_cmp_eq_u32_e64 s[4:5], s35, v3
	v_add_f32_e32 v165, 0, v0
	v_add_f32_e32 v165, v165, v2
	s_and_b64 s[4:5], vcc, s[4:5]
	v_cmp_eq_u32_e32 vcc, s35, v5
	v_add_f32_e32 v165, v165, v4
	s_nop 0
	s_and_b64 s[4:5], s[4:5], vcc
	v_cmp_eq_u32_e32 vcc, s35, v167
	v_add_f32_e32 v165, v165, v166
	v_fmamk_f32 v165, v165, 0x3a800000, v251
	s_and_b64 s[4:5], s[4:5], vcc
	s_orn2_b64 s[4:5], s[4:5], exec

.LBB0_999:
	ds_read_addtid_b32 v0 offset:0
	ds_read_addtid_b32 v1 offset:2048
	ds_read_addtid_b32 v2 offset:4096
	ds_read_addtid_b32 v3 offset:6144
	ds_read_addtid_b32 v4 offset:8192
	ds_read_addtid_b32 v5 offset:10240
	s_waitcnt lgkmcnt(0)
	s_mov_b32 m0, s101
	s_nop 0
	s_and_saveexec_b64 s[4:5], s[2:3]
	s_cbranch_execz .LBB0_1001
	v_rsq_f32_e32 v162, v165
	v_lshl_add_u32 v163, v254, 2, 0
	ds_write_b32 v163, v162 offset:4096
